# natten local blocks: 8 exec-masked serialized bias LDS reads -> unconditional reads, one wait, fmac + cndmask
# speedup vs baseline: 1.0201x; 1.0013x over previous
.LBB0_1556:
	s_min_i32 s4, s53, s52
	s_lshl_b32 s4, s4, 6
	s_or_b32 s4, s4, s56
	v_add_u32_e32 v2, s4, v1
	v_lshlrev_b64 v[100:101], 12, v[2:3]
	v_lshl_add_u64 v[108:109], v[164:165], 0, v[100:101]
	v_add_co_u32_e32 v112, vcc, s40, v108
	s_lshl_b32 s4, s4, 1
	s_nop 0
	v_addc_co_u32_e32 v113, vcc, 0, v109, vcc
	v_lshl_add_u64 v[148:149], v[170:171], 0, s[4:5]
	v_add_co_u32_e32 v152, vcc, s37, v148
	s_waitcnt vmcnt(5)
	v_mov_b32_e32 v128, v182
	v_addc_co_u32_e32 v153, vcc, 0, v149, vcc
	v_mov_b32_e32 v129, v183
	v_mov_b32_e32 v130, v180
	v_mov_b32_e32 v131, v181
	s_waitcnt vmcnt(4)
	v_mov_b32_e32 v124, v186
	v_mov_b32_e32 v125, v187
	v_mov_b32_e32 v126, v158
	v_mov_b32_e32 v127, v159
	global_load_dwordx4 v[100:103], v[108:109], off offset:2048
	global_load_dwordx4 v[104:107], v[108:109], off offset:2112
	s_nop 0
	global_load_dwordx4 v[108:111], v[112:113], off offset:2048
	s_nop 0
	global_load_dwordx4 v[112:115], v[112:113], off offset:2112
	v_lshl_add_u64 v[150:151], v[148:149], 0, s[10:11]
	global_load_dwordx2 v[182:183], v[148:149], off
	global_load_dwordx2 v[180:181], v[148:149], off offset:32
	global_load_dwordx2 v[186:187], v[152:153], off
	global_load_dwordx2 v[158:159], v[150:151], off offset:32
	v_add_co_u32_e32 v152, vcc, s41, v148
	v_lshl_add_u64 v[150:151], v[148:149], 0, s[12:13]
	s_nop 0
	v_addc_co_u32_e32 v153, vcc, 0, v149, vcc
	v_lshl_add_u64 v[154:155], v[148:149], 0, s[14:15]
	v_add_co_u32_e32 v148, vcc, 0x186000, v148
	s_waitcnt vmcnt(11)
	v_mov_b32_e32 v120, v162
	v_mov_b32_e32 v121, v163
	s_waitcnt vmcnt(8)
	v_mov_b32_e32 v122, v184
	v_mov_b32_e32 v123, v185
	v_mov_b32_e32 v116, v160
	v_mov_b32_e32 v117, v161
	v_mov_b32_e32 v118, v156
	v_mov_b32_e32 v119, v157
	v_addc_co_u32_e32 v149, vcc, 0, v149, vcc
	global_load_dwordx2 v[162:163], v[152:153], off
	global_load_dwordx2 v[160:161], v[148:149], off
	global_load_dwordx2 v[156:157], v[154:155], off offset:32
	global_load_dwordx2 v[184:185], v[150:151], off offset:32
	s_add_i32 s4, s53, -1
	s_cmp_lt_u32 s4, s49
	s_cselect_b64 s[30:31], -1, 0
	s_cmp_gt_u32 s4, s57
	s_cselect_b64 s[70:71], -1, 0
	s_or_b64 s[30:31], s[30:31], s[70:71]
	s_and_b64 vcc, exec, s[30:31]
	s_cbranch_vccnz .LBB0_1576
	s_waitcnt vmcnt(12)
	v_mfma_f32_16x16x32_bf16 v[148:151], v[144:147], v[56:59], 0
	v_mov_b32_e32 v2, 0xf149f2ca
	v_mov_b32_e32 v216, 0xf149f2ca
	v_mfma_f32_16x16x32_bf16 v[152:155], v[140:143], v[60:63], v[148:151]
	v_mfma_f32_16x16x32_bf16 v[148:151], v[136:139], v[56:59], 0
	v_mfma_f32_16x16x32_bf16 v[148:151], v[132:135], v[60:63], v[148:151]
	v_add_u32_e32 v236, s68, v211
	ds_read_b32 v236, v236
	v_add_u32_e32 v217, s68, v212
	ds_read_b32 v237, v217
	v_add_u32_e32 v238, s68, v213
	ds_read_b32 v238, v238
	ds_read_b32 v239, v217 offset:4
	v_add_u32_e32 v240, s68, v214
	ds_read_b32 v240, v240
	ds_read_b32 v241, v217 offset:8
	v_add_u32_e32 v242, s68, v215
	ds_read_b32 v242, v242
	ds_read_b32 v243, v217 offset:12
	v_mov_b32_e32 v244, 0xf149f2ca
	s_waitcnt lgkmcnt(0)
	v_fmac_f32_e32 v236, 0x3e000000, v152
	v_cndmask_b32_e64 v216, v244, v236, s[16:17]
	v_fmac_f32_e32 v237, 0x3e000000, v148
	v_cndmask_b32_e64 v2, v244, v237, s[18:19]
	v_fmac_f32_e32 v238, 0x3e000000, v153
	v_cndmask_b32_e64 v152, v244, v238, s[20:21]
	v_fmac_f32_e32 v239, 0x3e000000, v149
	v_cndmask_b32_e64 v148, v244, v239, s[22:23]
	v_fmac_f32_e32 v240, 0x3e000000, v154
	v_cndmask_b32_e64 v153, v244, v240, s[24:25]
	v_fmac_f32_e32 v241, 0x3e000000, v150
	v_cndmask_b32_e64 v149, v244, v241, s[26:27]
	v_fmac_f32_e32 v242, 0x3e000000, v155
	v_cndmask_b32_e64 v154, v244, v242, s[28:29]
	v_fmac_f32_e32 v243, 0x3e000000, v151
	v_cndmask_b32_e64 v150, v244, v243, s[0:1]
	v_max_f32_e32 v151, v152, v152
	v_max_f32_e32 v155, v216, v216
	v_max_f32_e32 v151, v155, v151
	v_max_f32_e32 v155, v154, v154
	v_max_f32_e32 v217, v153, v153
	v_max_f32_e32 v155, v217, v155
	v_max_f32_e32 v217, v150, v150
	v_max_f32_e32 v218, v149, v149
	v_max_f32_e32 v217, v218, v217
	v_max3_f32 v217, v2, v148, v217
	v_max3_f32 v155, v151, v155, v217
	v_add_f32_e32 v151, 0x41000000, v209
	v_cmp_gt_f32_e32 vcc, v155, v151
	s_cbranch_vccz .LBB0_1575
	ds_bpermute_b32 v217, v193, v155
	v_max_f32_e32 v155, v155, v155
	s_waitcnt lgkmcnt(0)
	v_max_f32_e32 v217, v217, v217
	v_max_f32_e32 v155, v155, v217
	ds_bpermute_b32 v217, v194, v155
	s_waitcnt lgkmcnt(0)
	v_max_f32_e32 v217, v217, v217
	v_max_f32_e32 v155, v155, v217
	v_cmp_gt_f32_e32 vcc, v155, v151
	s_nop 1
	v_cndmask_b32_e32 v151, v209, v155, vcc
	v_sub_f32_e32 v155, v209, v151
	v_mul_f32_e32 v155, 0x3fb8aa3b, v155
	v_exp_f32_e32 v155, v155
	v_mov_b32_e32 v209, v151
	ds_bpermute_b32 v218, v195, v155
	ds_bpermute_b32 v220, v197, v155
	ds_bpermute_b32 v221, v198, v155
	ds_bpermute_b32 v219, v196, v155
	v_mul_f32_e32 v179, v179, v155
	s_waitcnt lgkmcnt(1)
	v_pk_mul_f32 v[98:99], v[98:99], v[220:221]
	s_waitcnt lgkmcnt(0)
	v_pk_mul_f32 v[96:97], v[96:97], v[218:219]
	v_pk_mul_f32 v[78:79], v[78:79], v[220:221]
	v_pk_mul_f32 v[76:77], v[76:77], v[218:219]
	v_pk_mul_f32 v[66:67], v[66:67], v[220:221]
	v_pk_mul_f32 v[64:65], v[64:65], v[218:219]
	v_pk_mul_f32 v[54:55], v[54:55], v[220:221]
	v_pk_mul_f32 v[52:53], v[52:53], v[218:219]

.LBB0_1576:
	s_cmp_lt_u32 s4, s58
	s_cselect_b64 s[30:31], -1, 0
	s_cmp_gt_u32 s4, s59
	s_cselect_b64 s[70:71], -1, 0
	s_or_b64 s[30:31], s[30:31], s[70:71]
	s_and_b64 vcc, exec, s[30:31]
	s_cbranch_vccnz .LBB0_1596
	s_waitcnt vmcnt(12)
	v_mfma_f32_16x16x32_bf16 v[148:151], v[144:147], v[68:71], 0
	v_mov_b32_e32 v2, 0xf149f2ca
	v_mov_b32_e32 v216, 0xf149f2ca
	v_mfma_f32_16x16x32_bf16 v[152:155], v[140:143], v[72:75], v[148:151]
	v_mfma_f32_16x16x32_bf16 v[148:151], v[136:139], v[68:71], 0
	v_mfma_f32_16x16x32_bf16 v[148:151], v[132:135], v[72:75], v[148:151]
	v_add_u32_e32 v236, s38, v210
	v_add_u32_e32 v236, 0x11724, v236
	ds_read_b32 v236, v236
	v_add_u32_e32 v237, s38, v210
	v_add_u32_e32 v237, 0x11764, v237
	ds_read_b32 v237, v237
	v_add_u32_e32 v238, s38, v210
	v_add_u32_e32 v238, 0x11728, v238
	ds_read_b32 v238, v238
	v_add_u32_e32 v239, s38, v210
	v_add_u32_e32 v239, 0x11768, v239
	ds_read_b32 v239, v239
	v_add_u32_e32 v240, s38, v210
	v_add_u32_e32 v240, 0x1172c, v240
	ds_read_b32 v240, v240
	v_add_u32_e32 v241, s38, v210
	v_add_u32_e32 v241, 0x1176c, v241
	ds_read_b32 v241, v241
	v_add_u32_e32 v242, s38, v210
	v_add_u32_e32 v242, 0x11730, v242
	ds_read_b32 v242, v242
	v_add_u32_e32 v243, s38, v210
	v_add_u32_e32 v243, 0x11770, v243
	ds_read_b32 v243, v243
	v_mov_b32_e32 v244, 0xf149f2ca
	s_waitcnt lgkmcnt(0)
	v_fmac_f32_e32 v236, 0x3e000000, v152
	v_cndmask_b32_e64 v216, v244, v236, s[16:17]
	v_fmac_f32_e32 v237, 0x3e000000, v148
	v_cndmask_b32_e64 v2, v244, v237, s[18:19]
	v_fmac_f32_e32 v238, 0x3e000000, v153
	v_cndmask_b32_e64 v152, v244, v238, s[20:21]
	v_fmac_f32_e32 v239, 0x3e000000, v149
	v_cndmask_b32_e64 v148, v244, v239, s[22:23]
	v_fmac_f32_e32 v240, 0x3e000000, v154
	v_cndmask_b32_e64 v153, v244, v240, s[24:25]
	v_fmac_f32_e32 v241, 0x3e000000, v150
	v_cndmask_b32_e64 v149, v244, v241, s[26:27]
	v_fmac_f32_e32 v242, 0x3e000000, v155
	v_cndmask_b32_e64 v154, v244, v242, s[28:29]
	v_fmac_f32_e32 v243, 0x3e000000, v151
	v_cndmask_b32_e64 v150, v244, v243, s[0:1]
	v_max_f32_e32 v151, v152, v152
	v_max_f32_e32 v155, v216, v216
	v_max_f32_e32 v151, v155, v151
	v_max_f32_e32 v155, v154, v154
	v_max_f32_e32 v217, v153, v153
	v_max_f32_e32 v155, v217, v155
	v_max_f32_e32 v217, v150, v150
	v_max_f32_e32 v218, v149, v149
	v_max_f32_e32 v217, v218, v217
	v_max3_f32 v217, v2, v148, v217
	v_max3_f32 v155, v151, v155, v217
	v_add_f32_e32 v151, 0x41000000, v208
	v_cmp_gt_f32_e32 vcc, v155, v151
	s_cbranch_vccz .LBB0_1595
	ds_bpermute_b32 v217, v193, v155
	v_max_f32_e32 v155, v155, v155
	s_waitcnt lgkmcnt(0)
	v_max_f32_e32 v217, v217, v217
	v_max_f32_e32 v155, v155, v217
	ds_bpermute_b32 v217, v194, v155
	s_waitcnt lgkmcnt(0)
	v_max_f32_e32 v217, v217, v217
	v_max_f32_e32 v155, v155, v217
	v_cmp_gt_f32_e32 vcc, v155, v151
	s_nop 1
	v_cndmask_b32_e32 v151, v208, v155, vcc
	v_sub_f32_e32 v155, v208, v151
	v_mul_f32_e32 v155, 0x3fb8aa3b, v155
	v_exp_f32_e32 v155, v155
	v_mov_b32_e32 v208, v151
	ds_bpermute_b32 v218, v195, v155
	ds_bpermute_b32 v220, v197, v155
	ds_bpermute_b32 v221, v198, v155
	ds_bpermute_b32 v219, v196, v155
	v_mul_f32_e32 v177, v177, v155
	s_waitcnt lgkmcnt(1)
	v_pk_mul_f32 v[50:51], v[50:51], v[220:221]
	s_waitcnt lgkmcnt(0)
	v_pk_mul_f32 v[48:49], v[48:49], v[218:219]
	v_pk_mul_f32 v[46:47], v[46:47], v[220:221]
	v_pk_mul_f32 v[44:45], v[44:45], v[218:219]
	v_pk_mul_f32 v[42:43], v[42:43], v[220:221]
	v_pk_mul_f32 v[40:41], v[40:41], v[218:219]
	v_pk_mul_f32 v[38:39], v[38:39], v[220:221]
	v_pk_mul_f32 v[36:37], v[36:37], v[218:219]

.LBB0_1596:
	s_cmp_lt_u32 s4, s60
	s_cselect_b64 s[30:31], -1, 0
	s_cmp_gt_u32 s4, s61
	s_cselect_b64 s[70:71], -1, 0
	s_or_b64 s[30:31], s[30:31], s[70:71]
	s_and_b64 vcc, exec, s[30:31]
	s_cbranch_vccnz .LBB0_1616
	s_waitcnt vmcnt(12)
	v_mfma_f32_16x16x32_bf16 v[148:151], v[144:147], v[80:83], 0
	v_mov_b32_e32 v2, 0xf149f2ca
	v_mov_b32_e32 v216, 0xf149f2ca
	v_mfma_f32_16x16x32_bf16 v[152:155], v[140:143], v[84:87], v[148:151]
	v_mfma_f32_16x16x32_bf16 v[148:151], v[136:139], v[80:83], 0
	v_mfma_f32_16x16x32_bf16 v[148:151], v[132:135], v[84:87], v[148:151]
	v_add_u32_e32 v236, s38, v210
	v_add_u32_e32 v236, 0x116a8, v236
	ds_read_b32 v236, v236
	v_add_u32_e32 v237, s38, v210
	v_add_u32_e32 v237, 0x116e8, v237
	ds_read_b32 v237, v237
	v_add_u32_e32 v238, s38, v210
	v_add_u32_e32 v238, 0x116ac, v238
	ds_read_b32 v238, v238
	v_add_u32_e32 v239, s38, v210
	v_add_u32_e32 v239, 0x116ec, v239
	ds_read_b32 v239, v239
	v_add_u32_e32 v240, s38, v210
	v_add_u32_e32 v240, 0x116b0, v240
	ds_read_b32 v240, v240
	v_add_u32_e32 v241, s38, v210
	v_add_u32_e32 v241, 0x116f0, v241
	ds_read_b32 v241, v241
	v_add_u32_e32 v242, s38, v210
	v_add_u32_e32 v242, 0x116b4, v242
	ds_read_b32 v242, v242
	v_add_u32_e32 v243, s38, v210
	v_add_u32_e32 v243, 0x116f4, v243
	ds_read_b32 v243, v243
	v_mov_b32_e32 v244, 0xf149f2ca
	s_waitcnt lgkmcnt(0)
	v_fmac_f32_e32 v236, 0x3e000000, v152
	v_cndmask_b32_e64 v216, v244, v236, s[16:17]
	v_fmac_f32_e32 v237, 0x3e000000, v148
	v_cndmask_b32_e64 v2, v244, v237, s[18:19]
	v_fmac_f32_e32 v238, 0x3e000000, v153
	v_cndmask_b32_e64 v152, v244, v238, s[20:21]
	v_fmac_f32_e32 v239, 0x3e000000, v149
	v_cndmask_b32_e64 v148, v244, v239, s[22:23]
	v_fmac_f32_e32 v240, 0x3e000000, v154
	v_cndmask_b32_e64 v153, v244, v240, s[24:25]
	v_fmac_f32_e32 v241, 0x3e000000, v150
	v_cndmask_b32_e64 v149, v244, v241, s[26:27]
	v_fmac_f32_e32 v242, 0x3e000000, v155
	v_cndmask_b32_e64 v154, v244, v242, s[28:29]
	v_fmac_f32_e32 v243, 0x3e000000, v151
	v_cndmask_b32_e64 v150, v244, v243, s[0:1]
	v_max_f32_e32 v151, v152, v152
	v_max_f32_e32 v155, v216, v216
	v_max_f32_e32 v151, v155, v151
	v_max_f32_e32 v155, v154, v154
	v_max_f32_e32 v217, v153, v153
	v_max_f32_e32 v155, v217, v155
	v_max_f32_e32 v217, v150, v150
	v_max_f32_e32 v218, v149, v149
	v_max_f32_e32 v217, v218, v217
	v_max3_f32 v217, v2, v148, v217
	v_max3_f32 v155, v151, v155, v217
	v_add_f32_e32 v151, 0x41000000, v207
	v_cmp_gt_f32_e32 vcc, v155, v151
	s_cbranch_vccz .LBB0_1615
	ds_bpermute_b32 v217, v193, v155
	v_max_f32_e32 v155, v155, v155
	s_waitcnt lgkmcnt(0)
	v_max_f32_e32 v217, v217, v217
	v_max_f32_e32 v155, v155, v217
	ds_bpermute_b32 v217, v194, v155
	s_waitcnt lgkmcnt(0)
	v_max_f32_e32 v217, v217, v217
	v_max_f32_e32 v155, v155, v217
	v_cmp_gt_f32_e32 vcc, v155, v151
	s_nop 1
	v_cndmask_b32_e32 v151, v207, v155, vcc
	v_sub_f32_e32 v155, v207, v151
	v_mul_f32_e32 v155, 0x3fb8aa3b, v155
	v_exp_f32_e32 v155, v155
	v_mov_b32_e32 v207, v151
	ds_bpermute_b32 v218, v195, v155
	ds_bpermute_b32 v220, v197, v155
	ds_bpermute_b32 v221, v198, v155
	ds_bpermute_b32 v219, v196, v155
	v_mul_f32_e32 v175, v175, v155
	s_waitcnt lgkmcnt(1)
	v_pk_mul_f32 v[34:35], v[34:35], v[220:221]
	s_waitcnt lgkmcnt(0)
	v_pk_mul_f32 v[32:33], v[32:33], v[218:219]
	v_pk_mul_f32 v[30:31], v[30:31], v[220:221]
	v_pk_mul_f32 v[28:29], v[28:29], v[218:219]
	v_pk_mul_f32 v[26:27], v[26:27], v[220:221]
	v_pk_mul_f32 v[24:25], v[24:25], v[218:219]
	v_pk_mul_f32 v[22:23], v[22:23], v[220:221]
	v_pk_mul_f32 v[20:21], v[20:21], v[218:219]

.LBB0_1616:
	s_cmp_lt_u32 s4, s62
	s_cselect_b64 s[30:31], -1, 0
	s_cmp_gt_u32 s4, s63
	s_cselect_b64 s[70:71], -1, 0
	s_or_b64 s[30:31], s[30:31], s[70:71]
	s_and_b64 vcc, exec, s[30:31]
	s_cbranch_vccnz .LBB0_1636
	s_waitcnt vmcnt(12)
	v_mfma_f32_16x16x32_bf16 v[144:147], v[144:147], v[88:91], 0
	v_mov_b32_e32 v2, 0xf149f2ca
	v_mfma_f32_16x16x32_bf16 v[140:143], v[140:143], v[92:95], v[144:147]
	v_mfma_f32_16x16x32_bf16 v[146:149], v[136:139], v[88:91], 0
	s_nop 4
	v_add_u32_e32 v144, s38, v210
	v_mov_b32_e32 v136, 0xf149f2ca
	v_mfma_f32_16x16x32_bf16 v[132:135], v[132:135], v[92:95], v[146:149]
	v_add_u32_e32 v236, 0x1162c, v144
	ds_read_b32 v236, v236
	v_add_u32_e32 v237, 0x1166c, v144
	ds_read_b32 v237, v237
	v_add_u32_e32 v238, 0x11630, v144
	ds_read_b32 v238, v238
	v_add_u32_e32 v239, 0x11670, v144
	ds_read_b32 v239, v239
	v_add_u32_e32 v240, 0x11634, v144
	ds_read_b32 v240, v240
	v_add_u32_e32 v241, 0x11674, v144
	ds_read_b32 v241, v241
	v_add_u32_e32 v242, 0x11638, v144
	ds_read_b32 v242, v242
	v_add_u32_e32 v243, 0x11678, v144
	ds_read_b32 v243, v243
	v_mov_b32_e32 v244, 0xf149f2ca
	s_waitcnt lgkmcnt(0)
	v_fmac_f32_e32 v236, 0x3e000000, v140
	v_cndmask_b32_e64 v136, v244, v236, s[16:17]
	v_fmac_f32_e32 v237, 0x3e000000, v132
	v_cndmask_b32_e64 v2, v244, v237, s[18:19]
	v_fmac_f32_e32 v238, 0x3e000000, v141
	v_cndmask_b32_e64 v137, v244, v238, s[20:21]
	v_fmac_f32_e32 v239, 0x3e000000, v133
	v_cndmask_b32_e64 v132, v244, v239, s[22:23]
	v_fmac_f32_e32 v240, 0x3e000000, v142
	v_cndmask_b32_e64 v138, v244, v240, s[24:25]
	v_fmac_f32_e32 v241, 0x3e000000, v134
	v_cndmask_b32_e64 v133, v244, v241, s[26:27]
	v_fmac_f32_e32 v242, 0x3e000000, v143
	v_cndmask_b32_e64 v139, v244, v242, s[28:29]
	v_fmac_f32_e32 v243, 0x3e000000, v135
	v_cndmask_b32_e64 v134, v244, v243, s[0:1]
	v_max_f32_e32 v135, v137, v137
	v_max_f32_e32 v140, v136, v136
	v_max_f32_e32 v135, v140, v135
	v_max_f32_e32 v140, v139, v139
	v_max_f32_e32 v141, v138, v138
	v_max_f32_e32 v140, v141, v140
	v_max_f32_e32 v141, v134, v134
	v_max_f32_e32 v142, v133, v133
	v_max_f32_e32 v141, v142, v141
	v_max3_f32 v141, v2, v132, v141
	v_max3_f32 v140, v135, v140, v141
	v_add_f32_e32 v135, 0x41000000, v206
	v_cmp_gt_f32_e32 vcc, v140, v135
	s_cbranch_vccz .LBB0_1635
	ds_bpermute_b32 v141, v193, v140
	v_max_f32_e32 v140, v140, v140
	s_waitcnt lgkmcnt(0)
	v_max_f32_e32 v141, v141, v141
	v_max_f32_e32 v140, v140, v141
	ds_bpermute_b32 v141, v194, v140
	s_waitcnt lgkmcnt(0)
	v_max_f32_e32 v141, v141, v141
	v_max_f32_e32 v140, v140, v141
	v_cmp_gt_f32_e32 vcc, v140, v135
	s_nop 1
	v_cndmask_b32_e32 v135, v206, v140, vcc
	v_sub_f32_e32 v140, v206, v135
	v_mul_f32_e32 v140, 0x3fb8aa3b, v140
	v_exp_f32_e32 v144, v140
	v_mov_b32_e32 v206, v135
	ds_bpermute_b32 v140, v195, v144
	ds_bpermute_b32 v142, v197, v144
	ds_bpermute_b32 v143, v198, v144
	ds_bpermute_b32 v141, v196, v144
	v_mul_f32_e32 v173, v173, v144
	s_waitcnt lgkmcnt(1)
	v_pk_mul_f32 v[18:19], v[18:19], v[142:143]
	s_waitcnt lgkmcnt(0)
	v_pk_mul_f32 v[16:17], v[16:17], v[140:141]
	v_pk_mul_f32 v[14:15], v[14:15], v[142:143]
	v_pk_mul_f32 v[12:13], v[12:13], v[140:141]
	v_pk_mul_f32 v[10:11], v[10:11], v[142:143]
	v_pk_mul_f32 v[8:9], v[8:9], v[140:141]
	v_pk_mul_f32 v[6:7], v[6:7], v[142:143]
	v_pk_mul_f32 v[4:5], v[4:5], v[140:141]
